# MLA unit prologue: opening LDS barrier taken after the Q/first-tile loads are issued (just before the first ds_write); on top of the row_scales wait+barrier removal
# speedup vs baseline: 1.0084x; 1.0084x over previous
; DI float bf2f(unsigned short u) { return __uint_as_float((unsigned)u << 16); }
; #define ATT_LBAR() asm volatile("s_waitcnt lgkmcnt(0)\n\ts_barrier" ::: "memory")
; template <int MODE> DI void attn_unit(int b, int qb, const bf16* Qb, int qpitch, const bf16* Kb, int kpitch, const bf16* VT, bf16* O, float* ssq, ...
;     ...
;     ATT_LBAR();
;     v8s qr[ND];
; #pragma unroll
;     for (int d0 = 0; d0 < ND; ++d0) qr[d0] = *(const v8s*)(Qb + (rowbase + q) * qpitch + 16 * d0 + 8 * hi);
;     const int kt_lo = (MODE == 0) ? (4 * qb - 2 > 0 ? 4 * qb - 2 : 0) : 0, kt_hi = 4 * qb + 3;
;     v4u kreg0, kreg1 = {}, vreg; float freg = 0.f;
;     const int krow0 = tid / PCS, kc0 = tid % PCS, krow1 = (tid + 512) / PCS, kc1 = (tid + 512) % PCS;
;     const int vd = tid >> 3, vc = tid & 7;
;     ...
;     constexpr bool REV = (MODE == 1);
;     const int ntile = kt_hi - kt_lo + 1;
;     float qn = 0.f;
;     if (REV) {
; #pragma unroll
;         for (int d0 = 0; d0 < ND; ++d0)
; #pragma unroll
;             for (int j = 0; j < 8; ++j) { const float f = bf2f((unsigned short)qr[d0][j]); qn += f * f; }
;         qn += __shfl_xor(qn, 32); qn = sqrtf(qn) * 1.01f;
;     }
;     ATT_LOAD(REV ? kt_hi : kt_lo); ATT_STORE(0);
;     ATT_LBAR();
.LBB0_457:
	s_and_b64 s[18:19], s[22:23], exec
	s_cselect_b32 s24, s58, s36
	s_lshl_b32 s69, s24, 8
	s_add_i32 s59, s69, s3
	v_or_b32_e32 v64, s59, v119
	v_lshl_add_u64 v[182:183], s[12:13], 0, v[64:65]
	v_mad_u64_u32 v[0:1], s[18:19], v182, s86, v[160:161]
	v_mad_i32_i24 v1, v183, s86, v1
	global_load_dwordx4 v[66:69], v[0:1], off offset:32
	global_load_dwordx4 v[70:73], v[0:1], off offset:64
	global_load_dwordx4 v[74:77], v[0:1], off offset:96
	global_load_dwordx4 v[78:81], v[0:1], off offset:128
	global_load_dwordx4 v[82:85], v[0:1], off offset:160
	global_load_dwordx4 v[86:89], v[0:1], off
	global_load_dwordx4 v[90:93], v[162:163], off
	s_waitcnt vmcnt(12)
	v_mov_b32_e32 v94, v65
	v_mov_b32_e32 v95, v65
	v_mov_b32_e32 v96, v65
	v_mov_b32_e32 v97, v65
	s_and_saveexec_b64 s[18:19], s[38:39]
	s_cbranch_execz .Lmla_p1
	global_load_dwordx4 v[94:97], v[164:165], off
	global_load_dwordx4 v[36:39], v[178:179], off
.Lmla_p1:
	s_or_b64 exec, exec, s[18:19]
	global_load_dwordx4 v[98:101], v[166:167], off
	global_load_dwordx4 v[32:35], v[180:181], off
	s_waitcnt vmcnt(0)
	s_waitcnt lgkmcnt(0)
	s_barrier
	ds_write_b128 v206, v[90:93]
	v_add_u32_e32 v159, 0x3400, v206
	ds_write_b128 v159, v[32:35]
	s_and_saveexec_b64 s[18:19], s[38:39]
	s_cbranch_execz .Lmla_p2
	ds_write_b128 v207, v[94:97]
	v_add_u32_e32 v159, 0x3400, v207
	ds_write_b128 v159, v[36:39]
